# phase C tokpost: the five serialized row loads issued up front, single wait
# speedup vs baseline: 1.0105x; 1.0031x over previous
.LBB0_207:
	s_or_b64 exec, exec, s[42:43]
	v_mov_b32_e32 v34, 0x3e38aa3b
	v_cndmask_b32_e32 v34, 1.0, v34, vcc
	v_pk_mul_f32 v[38:39], v[34:35], v[16:17] op_sel_hi:[0,1]
	v_add_u32_e32 v16, 0x100, v74
	v_cndmask_b32_e64 v16, v74, v16, s[40:41]
	v_ashrrev_i32_e32 v17, 31, v16
	v_mov_b32_e32 v79, 0xb1b4000
	v_pk_mul_f32 v[0:1], v[34:35], v[0:1] op_sel_hi:[0,1]
	v_pk_mul_f32 v[2:3], v[34:35], v[2:3] op_sel_hi:[0,1]
	v_pk_mul_f32 v[4:5], v[34:35], v[4:5] op_sel_hi:[0,1]
	v_pk_mul_f32 v[6:7], v[34:35], v[6:7] op_sel_hi:[0,1]
	v_pk_mul_f32 v[8:9], v[34:35], v[8:9] op_sel_hi:[0,1]
	v_pk_mul_f32 v[10:11], v[34:35], v[10:11] op_sel_hi:[0,1]
	v_pk_mul_f32 v[12:13], v[34:35], v[12:13] op_sel_hi:[0,1]
	v_pk_mul_f32 v[14:15], v[34:35], v[14:15] op_sel_hi:[0,1]
	v_pk_mul_f32 v[18:19], v[34:35], v[18:19] op_sel_hi:[0,1]
	v_pk_mul_f32 v[20:21], v[34:35], v[20:21] op_sel_hi:[0,1]
	v_pk_mul_f32 v[22:23], v[34:35], v[22:23] op_sel_hi:[0,1]
	v_pk_mul_f32 v[24:25], v[34:35], v[24:25] op_sel_hi:[0,1]
	v_pk_mul_f32 v[26:27], v[34:35], v[26:27] op_sel_hi:[0,1]
	v_pk_mul_f32 v[28:29], v[34:35], v[28:29] op_sel_hi:[0,1]
	v_pk_mul_f32 v[30:31], v[34:35], v[30:31] op_sel_hi:[0,1]
	v_pk_mul_f32 v[40:41], v[34:35], v[94:95] op_sel_hi:[0,1]
	v_pk_mul_f32 v[42:43], v[34:35], v[92:93] op_sel_hi:[0,1]
	v_pk_mul_f32 v[56:57], v[34:35], v[90:91] op_sel_hi:[0,1]
	v_pk_mul_f32 v[58:59], v[34:35], v[88:89] op_sel_hi:[0,1]
	v_pk_mul_f32 v[48:49], v[34:35], v[48:49] op_sel_hi:[0,1]
	v_pk_mul_f32 v[50:51], v[34:35], v[50:51] op_sel_hi:[0,1]
	v_pk_mul_f32 v[52:53], v[34:35], v[52:53] op_sel_hi:[0,1]
	v_pk_mul_f32 v[54:55], v[34:35], v[54:55] op_sel_hi:[0,1]
	v_pk_mul_f32 v[60:61], v[34:35], v[96:97] op_sel_hi:[0,1]
	v_pk_mul_f32 v[62:63], v[34:35], v[98:99] op_sel_hi:[0,1]
	v_pk_mul_f32 v[80:81], v[34:35], v[100:101] op_sel_hi:[0,1]
	v_pk_mul_f32 v[82:83], v[34:35], v[102:103] op_sel_hi:[0,1]
	v_pk_mul_f32 v[44:45], v[34:35], v[44:45] op_sel_hi:[0,1]
	v_pk_mul_f32 v[46:47], v[34:35], v[46:47] op_sel_hi:[0,1]
	v_pk_mul_f32 v[36:37], v[34:35], v[36:37] op_sel_hi:[0,1]
	v_pk_mul_f32 v[32:33], v[34:35], v[32:33] op_sel_hi:[0,1]
	v_cndmask_b32_e32 v35, v17, v75, vcc
	v_cndmask_b32_e32 v34, v16, v74, vcc
	v_cndmask_b32_e32 v128, v79, v250, vcc
	v_lshl_add_u64 v[84:85], s[82:83], 0, v[128:129]
	v_lshlrev_b64 v[34:35], 10, v[34:35]
	v_lshl_add_u64 v[34:35], v[84:85], 0, v[34:35]
	v_mov_b32_e32 v79, v129
	v_lshl_add_u64 v[34:35], v[34:35], 0, v[78:79]
	v_cvt_pk_bf16_f32 v0, v0, v1
	v_cvt_pk_bf16_f32 v1, v2, v3
	v_cvt_pk_bf16_f32 v2, v4, v5
	v_cvt_pk_bf16_f32 v3, v6, v7
	global_store_dwordx4 v[34:35], v[0:3], off
	v_pk_mov_b32 v[4:5], v[58:59], v[58:59] op_sel:[1,0]
	v_lshlrev_b32_e32 v6, 3, v133
	v_cvt_pk_bf16_f32 v0, v8, v9
	v_cvt_pk_bf16_f32 v1, v10, v11
	v_cvt_pk_bf16_f32 v2, v12, v13
	v_cvt_pk_bf16_f32 v3, v14, v15
	global_store_dwordx4 v[34:35], v[0:3], off offset:16
	s_nop 1
	v_cvt_pk_bf16_f32 v0, v38, v39
	v_cvt_pk_bf16_f32 v1, v18, v19
	v_cvt_pk_bf16_f32 v2, v20, v21
	v_cvt_pk_bf16_f32 v3, v22, v23
	global_store_dwordx4 v[34:35], v[0:3], off offset:32
	s_nop 1
	v_cvt_pk_bf16_f32 v0, v24, v25
	v_cvt_pk_bf16_f32 v1, v26, v27
	v_cvt_pk_bf16_f32 v2, v28, v29
	v_cvt_pk_bf16_f32 v3, v30, v31
	global_store_dwordx4 v[34:35], v[0:3], off offset:48
	s_nop 1
	v_pk_mov_b32 v[0:1], v[40:41], v[40:41] op_sel:[1,0]
	v_pk_mov_b32 v[2:3], v[42:43], v[42:43] op_sel:[1,0]
	v_cvt_pk_bf16_f32 v0, v0, v1
	v_cvt_pk_bf16_f32 v1, v2, v3
	v_pk_mov_b32 v[2:3], v[56:57], v[56:57] op_sel:[1,0]
	s_nop 0
	v_cvt_pk_bf16_f32 v2, v2, v3
	v_cvt_pk_bf16_f32 v3, v4, v5
	global_store_dwordx4 v[34:35], v[0:3], off offset:64
	v_and_b32_e32 v4, 0x1f8, v6
	v_lshlrev_b32_e32 v128, 1, v4
	v_cvt_pk_bf16_f32 v0, v48, v49
	v_cvt_pk_bf16_f32 v1, v50, v51
	v_cvt_pk_bf16_f32 v2, v52, v53
	v_cvt_pk_bf16_f32 v3, v54, v55
	global_store_dwordx4 v[34:35], v[0:3], off offset:80
	v_lshlrev_b32_e32 v4, 2, v4
	s_nop 0
	v_cvt_pk_bf16_f32 v0, v60, v61
	v_cvt_pk_bf16_f32 v1, v62, v63
	v_cvt_pk_bf16_f32 v2, v80, v81
	v_cvt_pk_bf16_f32 v3, v82, v83
	global_store_dwordx4 v[34:35], v[0:3], off offset:96
	s_nop 1
	v_cvt_pk_bf16_f32 v0, v44, v45
	v_cvt_pk_bf16_f32 v1, v46, v47
	v_cvt_pk_bf16_f32 v2, v36, v37
	v_cvt_pk_bf16_f32 v3, v32, v33
	global_store_dwordx4 v[34:35], v[0:3], off offset:112
	s_nop 1
	v_ashrrev_i32_e32 v20, 6, v133
	v_add_u32_e32 v20, s24, v20
	v_mov_b64_e32 v[22:23], s[70:71]
	v_mad_i64_i32 v[22:23], s[40:41], v20, s58, v[22:23]
	v_lshl_add_u64 v[22:23], v[22:23], 0, v[128:129]
	v_add_co_u32_e32 v22, vcc, 0x1000, v22
	s_nop 1
	v_addc_co_u32_e32 v23, vcc, 0, v23, vcc
	global_load_dwordx4 v[40:43], v[22:23], off offset:2432
	v_add_u32_e32 v20, 0x100, v133
	v_ashrrev_i32_e32 v20, 6, v20
	v_add_u32_e32 v20, s24, v20
	v_mov_b64_e32 v[22:23], s[70:71]
	v_mad_i64_i32 v[22:23], s[40:41], v20, s58, v[22:23]
	v_lshl_add_u64 v[22:23], v[22:23], 0, v[128:129]
	v_add_co_u32_e32 v22, vcc, 0x1000, v22
	s_nop 1
	v_addc_co_u32_e32 v23, vcc, 0, v23, vcc
	global_load_dwordx4 v[44:47], v[22:23], off offset:2432
	v_add_u32_e32 v20, 0x200, v133
	v_ashrrev_i32_e32 v20, 6, v20
	v_add_u32_e32 v20, s24, v20
	v_mov_b64_e32 v[22:23], s[70:71]
	v_mad_i64_i32 v[22:23], s[40:41], v20, s58, v[22:23]
	v_lshl_add_u64 v[22:23], v[22:23], 0, v[128:129]
	v_add_co_u32_e32 v22, vcc, 0x1000, v22
	s_nop 1
	v_addc_co_u32_e32 v23, vcc, 0, v23, vcc
	global_load_dwordx4 v[48:51], v[22:23], off offset:2432
	v_add_u32_e32 v20, 0x300, v133
	v_ashrrev_i32_e32 v20, 6, v20
	v_add_u32_e32 v20, s24, v20
	v_mov_b64_e32 v[22:23], s[70:71]
	v_mad_i64_i32 v[22:23], s[40:41], v20, s58, v[22:23]
	v_lshl_add_u64 v[22:23], v[22:23], 0, v[128:129]
	v_add_co_u32_e32 v22, vcc, 0x1000, v22
	s_nop 1
	v_addc_co_u32_e32 v23, vcc, 0, v23, vcc
	global_load_dwordx4 v[52:55], v[22:23], off offset:2432
	v_cmp_gt_i32_e32 vcc, 64, v133
	s_and_saveexec_b64 s[42:43], vcc
	s_cbranch_execz .Ltp_no4
	v_ashrrev_i32_e32 v20, 2, v133
	v_add_u32_e32 v20, s24, v20
	v_mov_b64_e32 v[22:23], s[70:71]
	v_and_b32_e32 v30, 24, v6
	v_mad_i64_i32 v[22:23], s[40:41], v20, s58, v[22:23]
	v_lshlrev_b32_e32 v30, 1, v30
	v_mov_b32_e32 v31, 0
	v_lshl_add_u64 v[22:23], v[22:23], 0, v[30:31]
	v_add_co_u32_e32 v22, vcc, 0x1000, v22
	s_nop 1
	v_addc_co_u32_e32 v23, vcc, 0, v23, vcc
	global_load_dwordx4 v[56:59], v[22:23], off offset:320
.Ltp_no4:
	s_or_b64 exec, exec, s[42:43]
	v_ashrrev_i32_e32 v0, 6, v133
	v_add_u32_e32 v5, s24, v0
	v_add_u32_e32 v7, 0x100, v5
	v_cmp_lt_i32_e64 s[40:41], s2, v5
	v_cmp_gt_i32_e32 vcc, s25, v5
	s_nop 0
	v_cndmask_b32_e64 v8, v5, v7, s[40:41]
	v_ashrrev_i32_e32 v9, 31, v8
	v_readlane_b32 s40, v253, 11
	v_lshlrev_b64 v[8:9], 10, v[8:9]
	v_readlane_b32 s41, v253, 12
	s_nop 1
	v_lshl_add_u64 v[8:9], s[40:41], 0, v[8:9]
	v_lshl_add_u64 v[8:9], v[8:9], 0, v[128:129]
	s_waitcnt vmcnt(0)
	v_mov_b32_e32 v0, v40
	v_mov_b32_e32 v1, v41
	v_mov_b32_e32 v2, v42
	v_mov_b32_e32 v3, v43
	global_store_dwordx4 v[8:9], v[0:3], off
	s_and_saveexec_b64 s[40:41], vcc
	s_cbranch_execz .LBB0_209
	v_lshl_add_u32 v7, v5, 1, s27
	v_and_b32_e32 v7, 0xfffffe00, v7
	v_add_u32_e32 v7, s30, v7
	v_and_or_b32 v12, v5, s26, v7
	v_ashrrev_i32_e32 v13, 31, v12
	v_readlane_b32 s42, v253, 39
	v_lshlrev_b64 v[12:13], 11, v[12:13]
	v_readlane_b32 s43, v253, 40
	v_mov_b32_e32 v5, v129
	v_lshlrev_b32_e32 v8, 16, v0
	v_lshl_add_u64 v[12:13], s[42:43], 0, v[12:13]
	v_and_b32_e32 v9, 0xffff0000, v0
	v_lshlrev_b32_e32 v10, 16, v1
	v_and_b32_e32 v11, 0xffff0000, v1
	v_lshl_add_u64 v[12:13], v[12:13], 0, v[4:5]
	v_lshlrev_b32_e32 v0, 16, v2
	v_and_b32_e32 v1, 0xffff0000, v2
	v_lshlrev_b32_e32 v2, 16, v3
	v_and_b32_e32 v3, 0xffff0000, v3
	global_store_dwordx4 v[12:13], v[8:11], off
	global_store_dwordx4 v[12:13], v[0:3], off offset:16
.LBB0_209:
	s_or_b64 exec, exec, s[40:41]
	s_nop 0
	v_add_u32_e32 v0, 0x100, v133
	v_ashrrev_i32_e32 v0, 6, v0
	v_add_u32_e32 v5, s24, v0
	v_add_u32_e32 v7, 0x100, v5
	v_cmp_lt_i32_e64 s[40:41], s2, v5
	v_cmp_gt_i32_e32 vcc, s25, v5
	s_nop 0
	v_cndmask_b32_e64 v8, v5, v7, s[40:41]
	v_ashrrev_i32_e32 v9, 31, v8
	v_readlane_b32 s40, v253, 11
	v_lshlrev_b64 v[8:9], 10, v[8:9]
	v_readlane_b32 s41, v253, 12
	s_nop 1
	v_lshl_add_u64 v[8:9], s[40:41], 0, v[8:9]
	v_lshl_add_u64 v[8:9], v[8:9], 0, v[128:129]
	v_mov_b32_e32 v0, v44
	v_mov_b32_e32 v1, v45
	v_mov_b32_e32 v2, v46
	v_mov_b32_e32 v3, v47
	global_store_dwordx4 v[8:9], v[0:3], off
	s_and_saveexec_b64 s[40:41], vcc
	s_cbranch_execz .LBB0_211
	v_lshl_add_u32 v7, v5, 1, s27
	v_and_b32_e32 v7, 0xfffffe00, v7
	v_add_u32_e32 v7, s30, v7
	v_and_or_b32 v12, v5, s26, v7
	v_ashrrev_i32_e32 v13, 31, v12
	v_readlane_b32 s42, v253, 39
	v_lshlrev_b64 v[12:13], 11, v[12:13]
	v_readlane_b32 s43, v253, 40
	v_mov_b32_e32 v5, v129
	v_lshlrev_b32_e32 v8, 16, v0
	v_lshl_add_u64 v[12:13], s[42:43], 0, v[12:13]
	v_and_b32_e32 v9, 0xffff0000, v0
	v_lshlrev_b32_e32 v10, 16, v1
	v_and_b32_e32 v11, 0xffff0000, v1
	v_lshl_add_u64 v[12:13], v[12:13], 0, v[4:5]
	v_lshlrev_b32_e32 v0, 16, v2
	v_and_b32_e32 v1, 0xffff0000, v2
	v_lshlrev_b32_e32 v2, 16, v3
	v_and_b32_e32 v3, 0xffff0000, v3
	global_store_dwordx4 v[12:13], v[8:11], off
	global_store_dwordx4 v[12:13], v[0:3], off offset:16
.LBB0_211:
	s_or_b64 exec, exec, s[40:41]
	s_nop 0
	v_add_u32_e32 v0, 0x200, v133
	v_ashrrev_i32_e32 v0, 6, v0
	v_add_u32_e32 v5, s24, v0
	v_add_u32_e32 v7, 0x100, v5
	v_cmp_lt_i32_e64 s[40:41], s2, v5
	v_cmp_gt_i32_e32 vcc, s25, v5
	s_nop 0
	v_cndmask_b32_e64 v8, v5, v7, s[40:41]
	v_ashrrev_i32_e32 v9, 31, v8
	v_readlane_b32 s40, v253, 11
	v_lshlrev_b64 v[8:9], 10, v[8:9]
	v_readlane_b32 s41, v253, 12
	s_nop 1
	v_lshl_add_u64 v[8:9], s[40:41], 0, v[8:9]
	v_lshl_add_u64 v[8:9], v[8:9], 0, v[128:129]
	v_mov_b32_e32 v0, v48
	v_mov_b32_e32 v1, v49
	v_mov_b32_e32 v2, v50
	v_mov_b32_e32 v3, v51
	global_store_dwordx4 v[8:9], v[0:3], off
	s_and_saveexec_b64 s[40:41], vcc
	s_cbranch_execz .LBB0_213
	v_lshl_add_u32 v7, v5, 1, s27
	v_and_b32_e32 v7, 0xfffffe00, v7
	v_add_u32_e32 v7, s30, v7
	v_and_or_b32 v12, v5, s26, v7
	v_ashrrev_i32_e32 v13, 31, v12
	v_readlane_b32 s42, v253, 39
	v_lshlrev_b64 v[12:13], 11, v[12:13]
	v_readlane_b32 s43, v253, 40
	v_mov_b32_e32 v5, v129
	v_lshlrev_b32_e32 v8, 16, v0
	v_lshl_add_u64 v[12:13], s[42:43], 0, v[12:13]
	v_and_b32_e32 v9, 0xffff0000, v0
	v_lshlrev_b32_e32 v10, 16, v1
	v_and_b32_e32 v11, 0xffff0000, v1
	v_lshl_add_u64 v[12:13], v[12:13], 0, v[4:5]
	v_lshlrev_b32_e32 v0, 16, v2
	v_and_b32_e32 v1, 0xffff0000, v2
	v_lshlrev_b32_e32 v2, 16, v3
	v_and_b32_e32 v3, 0xffff0000, v3
	global_store_dwordx4 v[12:13], v[8:11], off
	global_store_dwordx4 v[12:13], v[0:3], off offset:16
.LBB0_213:
	s_or_b64 exec, exec, s[40:41]
	s_nop 0
	v_add_u32_e32 v0, 0x300, v133
	v_ashrrev_i32_e32 v0, 6, v0
	v_add_u32_e32 v5, s24, v0
	v_add_u32_e32 v7, 0x100, v5
	v_cmp_lt_i32_e64 s[40:41], s2, v5
	v_cmp_gt_i32_e32 vcc, s25, v5
	s_nop 0
	v_cndmask_b32_e64 v8, v5, v7, s[40:41]
	v_ashrrev_i32_e32 v9, 31, v8
	v_readlane_b32 s40, v253, 11
	v_lshlrev_b64 v[8:9], 10, v[8:9]
	v_readlane_b32 s41, v253, 12
	s_nop 1
	v_lshl_add_u64 v[8:9], s[40:41], 0, v[8:9]
	v_lshl_add_u64 v[8:9], v[8:9], 0, v[128:129]
	v_mov_b32_e32 v0, v52
	v_mov_b32_e32 v1, v53
	v_mov_b32_e32 v2, v54
	v_mov_b32_e32 v3, v55
	global_store_dwordx4 v[8:9], v[0:3], off
	s_and_saveexec_b64 s[40:41], vcc
	s_cbranch_execz .LBB0_215
	v_lshl_add_u32 v7, v5, 1, s27
	v_and_b32_e32 v7, 0xfffffe00, v7
	v_add_u32_e32 v7, s30, v7
	v_and_or_b32 v12, v5, s26, v7
	v_ashrrev_i32_e32 v13, 31, v12
	v_readlane_b32 s42, v253, 39
	v_lshlrev_b64 v[12:13], 11, v[12:13]
	v_readlane_b32 s43, v253, 40
	v_mov_b32_e32 v5, v129
	v_lshlrev_b32_e32 v8, 16, v0
	v_lshl_add_u64 v[12:13], s[42:43], 0, v[12:13]
	v_and_b32_e32 v9, 0xffff0000, v0
	v_lshlrev_b32_e32 v10, 16, v1
	v_and_b32_e32 v11, 0xffff0000, v1
	v_lshl_add_u64 v[4:5], v[12:13], 0, v[4:5]
	v_lshlrev_b32_e32 v0, 16, v2
	v_and_b32_e32 v1, 0xffff0000, v2
	v_lshlrev_b32_e32 v2, 16, v3
	v_and_b32_e32 v3, 0xffff0000, v3
	global_store_dwordx4 v[4:5], v[8:11], off
	global_store_dwordx4 v[4:5], v[0:3], off offset:16
.LBB0_215:
	s_or_b64 exec, exec, s[40:41]
	v_cmp_gt_i32_e32 vcc, 64, v133
	s_and_saveexec_b64 s[42:43], vcc
	s_cbranch_execz .LBB0_218
	v_ashrrev_i32_e32 v0, 2, v133
	v_add_u32_e32 v5, s24, v0
	v_and_b32_e32 v4, 24, v6
	v_lshlrev_b32_e32 v128, 1, v4
	v_add_u32_e32 v6, 0x100, v5
	v_cmp_lt_i32_e64 s[40:41], s2, v5
	s_movk_i32 s24, 0x400
	v_cmp_gt_i32_e32 vcc, s24, v5
	v_cndmask_b32_e64 v6, v5, v6, s[40:41]
	v_ashrrev_i32_e32 v7, 31, v6
	v_readlane_b32 s24, v253, 19
	v_lshlrev_b64 v[6:7], 6, v[6:7]
	v_readlane_b32 s25, v253, 20
	s_nop 1
	v_lshl_add_u64 v[6:7], s[24:25], 0, v[6:7]
	v_lshl_add_u64 v[6:7], v[6:7], 0, v[128:129]
	v_mov_b32_e32 v0, v56
	v_mov_b32_e32 v1, v57
	v_mov_b32_e32 v2, v58
	v_mov_b32_e32 v3, v59
	global_store_dwordx4 v[6:7], v[0:3], off
	s_and_b64 exec, exec, vcc
	s_cbranch_execz .LBB0_218
	v_lshl_add_u32 v10, v5, 1, s27
	v_and_b32_e32 v10, 0xfffffe00, v10
	v_add_u32_e32 v10, s30, v10
	v_and_or_b32 v10, v5, s26, v10
	v_ashrrev_i32_e32 v11, 31, v10
	v_readlane_b32 s24, v253, 41
	v_lshlrev_b64 v[10:11], 7, v[10:11]
	v_readlane_b32 s25, v253, 42
	v_lshlrev_b32_e32 v128, 2, v4
	v_lshlrev_b32_e32 v6, 16, v0
	v_lshl_add_u64 v[10:11], s[24:25], 0, v[10:11]
	v_and_b32_e32 v7, 0xffff0000, v0
	v_lshlrev_b32_e32 v8, 16, v1
	v_and_b32_e32 v9, 0xffff0000, v1
	v_lshl_add_u64 v[4:5], v[10:11], 0, v[128:129]
	v_lshlrev_b32_e32 v0, 16, v2
	v_and_b32_e32 v1, 0xffff0000, v2
	v_lshlrev_b32_e32 v2, 16, v3
	v_and_b32_e32 v3, 0xffff0000, v3
	global_store_dwordx4 v[4:5], v[6:9], off
	global_store_dwordx4 v[4:5], v[0:3], off offset:16
